# attention<true>: first four V fragment reads of each key tile issued right after its last QK MFMA (LDS latency hidden under the softmax VALU)
# speedup vs baseline: 1.0012x; 1.0007x over previous
; #define LAS __attribute__((address_space(3)))
; __device__ __forceinline__ unsigned pk2(float lo, float hi) { f32x2_t v = {lo, hi}; bf16x2_t b = __builtin_convertvector(v, bf16x2_t); return __builtin_bit_cast(unsigned, b); }
; __device__ __forceinline__ s16x4 trrd(LAS const unsigned char* p) { return __builtin_bit_cast(s16x4, __builtin_amdgcn_ds_read_tr16_b64_v4i16((LAS v4i16_t*)p)); }
; template <bool FUSED> __device__ __forceinline__ void attn_phase(const Args& a, LAS unsigned char* lds, int tid, int lane, int wave) {
;     ...
;         for (int j = 0; j < 5; ++j) {
;             f32x16 st;
; #pragma unroll
;             for (int i = 0; i < 16; ++i) st[i] = -mb;
;             LAS const unsigned char* kp = lds + (32 * wave + 32 * j + l31) * KP + 16 * h;
; #pragma unroll
;             for (int ks = 0; ks < 4; ++ks) { const bf16x8 kf = *(LAS const bf16x8*)(kp + 32 * ks); st = __builtin_amdgcn_mfma_f32_32x32x16_bf16(kf, qf[ks], st, 0, 0, 0); }
;             sum += attn_tile_exp(st, j, tlf, bsl, rlo, rhi);
; #pragma unroll
;             for (int s2 = 0; s2 < 2; ++s2) { u32x4 pw; pw.x = pk2(st[8 * s2 + 0], st[8 * s2 + 1]); pw.y = pk2(st[8 * s2 + 2], st[8 * s2 + 3]); pw.z = pk2(st[8 * s2 + 4], st[8 * s2 + 5]); pw.w = pk2(st[8 * s2 + 6], st[8 * s2 + 7]);
;                 const bf16x8 pf = __builtin_bit_cast(bf16x8, pw);
;                 LAS const unsigned char* vp = lds + LDS_VOFF + (32 * wave + 32 * j + 16 * s2 + 4 * h + q) * VP + 32 * blk + 8 * p;
; #pragma unroll
;                 for (int dt = 0; dt < 2; ++dt) { const s16x4 lo = trrd(vp + dt * 64), hi = trrd(vp + 8 * VP + dt * 64);
;                     const bf16x8 vf = __builtin_shufflevector(lo, hi, 0, 1, 2, 3, 4, 5, 6, 7);
;                     o[dt] = __builtin_amdgcn_mfma_f32_32x32x16_bf16(vf, pf, o[dt], 0, 0, 0); } }
;             __builtin_amdgcn_sched_barrier(0);
;         }
.Lattn2_join:
	v_xor_b32_e32 v32, 0x80000000, v229
	v_mov_b32_e32 v33, v32
	v_mov_b32_e32 v34, v32
	v_mov_b32_e32 v35, v32
	v_mov_b32_e32 v36, v32
	v_mov_b32_e32 v37, v32
	v_mov_b32_e32 v38, v32
	v_mov_b32_e32 v39, v32
	v_mov_b32_e32 v40, v32
	v_mov_b32_e32 v41, v32
	v_mov_b32_e32 v42, v32
	v_mov_b32_e32 v43, v32
	v_mov_b32_e32 v44, v32
	v_mov_b32_e32 v45, v32
	v_mov_b32_e32 v46, v32
	v_mov_b32_e32 v47, v32
	s_and_b32 s8, s8, 31
	s_waitcnt lgkmcnt(0)
	v_mfma_f32_32x32x16_bf16 v[0:15], v[20:23], v[96:99], v[32:47]
	ds_read_b128 v[20:23], v206 offset:64
	v_cvt_f32_ubyte0_e32 v16, s6
	v_exp_f32_e64 v29, -v16
	v_mfma_f32_32x32x16_bf16 v[0:15], v[24:27], v[100:103], v[0:15]
	s_lshl_b32 s66, s8, 8
	ds_read_b128 v[16:19], v206 offset:96
	s_add_i32 s66, s66, s48
	s_lshl_b32 s9, 1, s7
	s_lshr_b32 s7, 0x2000, s7
	s_waitcnt lgkmcnt(1)
	v_mfma_f32_32x32x16_bf16 v[0:15], v[20:23], v[104:107], v[0:15]
	v_or_b32_e32 v62, s66, v145
	v_sub_u32_e32 v20, 0, v62
	v_xad_u32 v21, v62, -1, s7
	v_cvt_f32_u32_e32 v24, s9
	v_cvt_f32_i32_e32 v171, v28
	v_max_i32_e32 v20, 0xffffffc0, v20
	v_min_i32_e32 v21, 64, v21
	s_waitcnt lgkmcnt(0)
	v_mfma_f32_32x32x16_bf16 v[0:15], v[16:19], v[108:111], v[0:15]
	ds_read_b64_tr_b16 v[128:129], v207 offset:55296
	ds_read_b64_tr_b16 v[130:131], v207 offset:56832
	ds_read_b64_tr_b16 v[134:135], v207 offset:56896
	ds_read_b64_tr_b16 v[132:133], v207 offset:55360
	v_readfirstlane_b32 s98, v62
	s_sub_i32 s99, s7, 64
	v_cvt_f32_i32_e32 v168, v20
	v_cvt_f32_i32_e32 v169, v21
	v_mul_f32_e32 v24, v29, v24
	v_add_f32_e32 v16, 0xc2800000, v171
	v_mul_f32_e32 v170, 0xbfb8aa3b, v24
	v_cmp_nge_f32_e32 vcc, v16, v168
	v_cmp_nle_f32_e64 s[6:7], v16, v169
	s_nop 4
	v_fma_f32 v0, v170, |v16|, v0
	s_or_b64 vcc, vcc, s[6:7]
	v_add_f32_e32 v17, 0xc27c0000, v171
	v_cndmask_b32_e32 v0, v0, v228, vcc
	v_cmp_nge_f32_e32 vcc, v17, v168
	v_cmp_nle_f32_e64 s[6:7], v17, v169
	v_fma_f32 v1, v170, |v17|, v1
	s_or_b64 vcc, vcc, s[6:7]
	v_cndmask_b32_e32 v1, v1, v228, vcc
	v_exp_f32_e32 v17, v1
	v_add_f32_e32 v1, 0xc2780000, v171
	v_cmp_nge_f32_e32 vcc, v1, v168
	v_cmp_nle_f32_e64 s[6:7], v1, v169
	v_fma_f32 v2, v170, |v1|, v2
	s_or_b64 vcc, vcc, s[6:7]
	v_cndmask_b32_e32 v1, v2, v228, vcc
	v_exp_f32_e32 v18, v1
	v_add_f32_e32 v1, 0xc2740000, v171
	v_cmp_nge_f32_e32 vcc, v1, v168
	v_cmp_nle_f32_e64 s[6:7], v1, v169
	v_fma_f32 v2, v170, |v1|, v3
	s_or_b64 vcc, vcc, s[6:7]
	v_cndmask_b32_e32 v1, v2, v228, vcc
	v_exp_f32_e32 v19, v1
	v_add_f32_e32 v1, 0xc2600000, v171
	v_cmp_nge_f32_e32 vcc, v1, v168
	v_cmp_nle_f32_e64 s[6:7], v1, v169
	v_fma_f32 v2, v170, |v1|, v4
	s_or_b64 vcc, vcc, s[6:7]
	v_cndmask_b32_e32 v1, v2, v228, vcc
	v_exp_f32_e32 v20, v1
	v_add_f32_e32 v1, 0xc25c0000, v171
	v_cmp_nge_f32_e32 vcc, v1, v168
	v_cmp_nle_f32_e64 s[6:7], v1, v169
	v_fma_f32 v2, v170, |v1|, v5
	s_or_b64 vcc, vcc, s[6:7]
	v_cndmask_b32_e32 v1, v2, v228, vcc
	v_exp_f32_e32 v21, v1
	v_add_f32_e32 v1, 0xc2580000, v171
	v_cmp_nge_f32_e32 vcc, v1, v168
	v_cmp_nle_f32_e64 s[6:7], v1, v169
	v_fma_f32 v2, v170, |v1|, v6
	s_or_b64 vcc, vcc, s[6:7]
	v_cndmask_b32_e32 v1, v2, v228, vcc
	v_exp_f32_e32 v16, v0
	v_exp_f32_e32 v22, v1
	v_add_f32_e32 v1, 0xc2540000, v171
	v_cmp_nge_f32_e32 vcc, v1, v168
	v_cmp_nle_f32_e64 s[6:7], v1, v169
	v_fma_f32 v2, v170, |v1|, v7
	s_or_b64 vcc, vcc, s[6:7]
	v_cndmask_b32_e32 v1, v2, v228, vcc
	v_add_f32_e32 v0, 0, v16
	v_exp_f32_e32 v7, v1
	v_add_f32_e32 v1, 0xc2400000, v171
	v_add_f32_e32 v0, v17, v0
	v_cmp_nge_f32_e32 vcc, v1, v168
	v_cmp_nle_f32_e64 s[6:7], v1, v169
	v_add_f32_e32 v0, v18, v0
	v_fma_f32 v2, v170, |v1|, v8
	s_or_b64 vcc, vcc, s[6:7]
	v_add_f32_e32 v0, v19, v0
	v_cndmask_b32_e32 v1, v2, v228, vcc
	v_add_f32_e32 v0, v20, v0
	v_exp_f32_e32 v52, v1
	v_add_f32_e32 v0, v21, v0
	v_add_f32_e32 v0, v22, v0
	v_add_f32_e32 v0, v7, v0
	v_add_f32_e32 v60, v52, v0
	v_add_f32_e32 v0, 0xc23c0000, v171
	v_cmp_nge_f32_e32 vcc, v0, v168
	v_cmp_nle_f32_e64 s[6:7], v0, v169
	v_fma_f32 v1, v170, |v0|, v9
	s_or_b64 vcc, vcc, s[6:7]
	v_cndmask_b32_e32 v0, v1, v228, vcc
	v_exp_f32_e32 v61, v0
	v_add_f32_e32 v0, 0xc2380000, v171
	v_cmp_nge_f32_e32 vcc, v0, v168
	v_cmp_nle_f32_e64 s[6:7], v0, v169
	v_fma_f32 v1, v170, |v0|, v10
	s_or_b64 vcc, vcc, s[6:7]
	v_cndmask_b32_e32 v0, v1, v228, vcc
	v_exp_f32_e32 v62, v0
	v_add_f32_e32 v0, 0xc2340000, v171
	v_cmp_nge_f32_e32 vcc, v0, v168
	v_cmp_nle_f32_e64 s[6:7], v0, v169
	v_fma_f32 v1, v170, |v0|, v11
	s_or_b64 vcc, vcc, s[6:7]
	v_cndmask_b32_e32 v0, v1, v228, vcc
	v_exp_f32_e32 v63, v0
	v_add_f32_e32 v0, 0xc2200000, v171
	v_cmp_nge_f32_e32 vcc, v0, v168
	v_cmp_nle_f32_e64 s[6:7], v0, v169
	v_fma_f32 v1, v170, |v0|, v12
	s_or_b64 vcc, vcc, s[6:7]
	v_cndmask_b32_e32 v0, v1, v228, vcc
	v_exp_f32_e32 v172, v0
	v_add_f32_e32 v0, 0xc21c0000, v171
	v_cmp_nge_f32_e32 vcc, v0, v168
	v_cmp_nle_f32_e64 s[6:7], v0, v169
	v_fma_f32 v1, v170, |v0|, v13
	s_or_b64 vcc, vcc, s[6:7]
	v_cndmask_b32_e32 v0, v1, v228, vcc
	v_exp_f32_e32 v173, v0
	v_add_f32_e32 v0, 0xc2180000, v171
	v_cmp_nge_f32_e32 vcc, v0, v168
	v_cmp_nle_f32_e64 s[6:7], v0, v169
	v_fma_f32 v1, v170, |v0|, v14
	s_or_b64 vcc, vcc, s[6:7]
	v_cndmask_b32_e32 v4, v1, v228, vcc
	v_add_f32_e32 v12, 0xc2140000, v171
	v_exp_f32_e32 v174, v4
	v_cvt_pk_bf16_f32 v4, v16, v17
	v_cvt_pk_bf16_f32 v5, v18, v19
	v_cvt_pk_bf16_f32 v6, v20, v21
	v_cvt_pk_bf16_f32 v7, v22, v7
	v_cmp_nge_f32_e32 vcc, v12, v168
	v_cmp_nle_f32_e64 s[6:7], v12, v169
	s_waitcnt lgkmcnt(2)
	v_mfma_f32_32x32x16_bf16 v[16:31], v[128:131], v[4:7], 0
	v_fma_f32 v0, v170, |v12|, v15
	s_or_b64 vcc, vcc, s[6:7]
	v_cndmask_b32_e32 v53, v0, v228, vcc
	ds_read_b64_tr_b16 v[48:49], v207 offset:58368
	ds_read_b64_tr_b16 v[50:51], v207 offset:59904
	v_exp_f32_e32 v175, v53
	ds_read_b64_tr_b16 v[58:59], v207 offset:59968
	ds_read_b64_tr_b16 v[56:57], v207 offset:58432
	v_cvt_pk_bf16_f32 v52, v52, v61
	s_waitcnt lgkmcnt(4)
	v_mfma_f32_32x32x16_bf16 v[0:15], v[132:135], v[4:7], 0
	v_cvt_pk_bf16_f32 v53, v62, v63
	v_cvt_pk_bf16_f32 v54, v172, v173
	v_cvt_pk_bf16_f32 v55, v174, v175
	s_waitcnt lgkmcnt(2)
	s_nop 0
	v_mfma_f32_32x32x16_bf16 v[16:31], v[48:51], v[52:55], v[16:31]
	v_add_f32_e32 v48, v61, v60
	v_add_f32_e32 v48, v62, v48
	v_add_f32_e32 v48, v63, v48
	v_add_f32_e32 v48, v172, v48
	v_add_f32_e32 v48, v173, v48
	v_add_f32_e32 v48, v174, v48
	v_add_f32_e32 v48, v175, v48
	s_waitcnt lgkmcnt(0)
	v_mfma_f32_32x32x16_bf16 v[0:15], v[56:59], v[52:55], v[0:15]
	v_add_f32_e32 v238, 0, v48
	s_cmp_lt_i32 s98, 32
	s_cbranch_scc1 .Lattn2_skip1
; #define LAS __attribute__((address_space(3)))
; __device__ __forceinline__ unsigned pk2(float lo, float hi) { f32x2_t v = {lo, hi}; bf16x2_t b = __builtin_convertvector(v, bf16x2_t); return __builtin_bit_cast(unsigned, b); }
; __device__ __forceinline__ s16x4 trrd(LAS const unsigned char* p) { return __builtin_bit_cast(s16x4, __builtin_amdgcn_ds_read_tr16_b64_v4i16((LAS v4i16_t*)p)); }
; template <bool FUSED> __device__ __forceinline__ void attn_phase(const Args& a, LAS unsigned char* lds, int tid, int lane, int wave) {
;     ...
;         for (int j = 0; j < 5; ++j) {
;             f32x16 st;
; #pragma unroll
;             for (int i = 0; i < 16; ++i) st[i] = -mb;
;             LAS const unsigned char* kp = lds + (32 * wave + 32 * j + l31) * KP + 16 * h;
; #pragma unroll
;             for (int ks = 0; ks < 4; ++ks) { const bf16x8 kf = *(LAS const bf16x8*)(kp + 32 * ks); st = __builtin_amdgcn_mfma_f32_32x32x16_bf16(kf, qf[ks], st, 0, 0, 0); }
;             sum += attn_tile_exp(st, j, tlf, bsl, rlo, rhi);
; #pragma unroll
;             for (int s2 = 0; s2 < 2; ++s2) { u32x4 pw; pw.x = pk2(st[8 * s2 + 0], st[8 * s2 + 1]); pw.y = pk2(st[8 * s2 + 2], st[8 * s2 + 3]); pw.z = pk2(st[8 * s2 + 4], st[8 * s2 + 5]); pw.w = pk2(st[8 * s2 + 6], st[8 * s2 + 7]);
;                 const bf16x8 pf = __builtin_bit_cast(bf16x8, pw);
;                 LAS const unsigned char* vp = lds + LDS_VOFF + (32 * wave + 32 * j + 16 * s2 + 4 * h + q) * VP + 32 * blk + 8 * p;
; #pragma unroll
;                 for (int dt = 0; dt < 2; ++dt) { const s16x4 lo = trrd(vp + dt * 64), hi = trrd(vp + 8 * VP + dt * 64);
;                     const bf16x8 vf = __builtin_shufflevector(lo, hi, 0, 1, 2, 3, 4, 5, 6, 7);
;                     o[dt] = __builtin_amdgcn_mfma_f32_32x32x16_bf16(vf, pf, o[dt], 0, 0, 0); } }
;             __builtin_amdgcn_sched_barrier(0);
;         }
	ds_read_b128 v[172:175], v208
	ds_read_b128 v[230:233], v208 offset:32
	v_add_f32_e32 v239, 0xc2000000, v171
	v_add_f32_e32 v240, 0xc1f80000, v171
	s_waitcnt lgkmcnt(1)
	v_mfma_f32_32x32x16_bf16 v[48:63], v[172:175], v[96:99], v[32:47]
	ds_read_b128 v[172:175], v208 offset:64
	ds_read_b128 v[234:237], v208 offset:96
	v_add_f32_e32 v241, 0xc1f00000, v171
	v_add_f32_e32 v242, 0xc1e80000, v171
	s_waitcnt lgkmcnt(2)
	v_mfma_f32_32x32x16_bf16 v[48:63], v[230:233], v[100:103], v[48:63]
	v_add_f32_e32 v230, 0xc1c00000, v171
	v_add_f32_e32 v231, 0xc1b80000, v171
	s_waitcnt lgkmcnt(1)
	v_mfma_f32_32x32x16_bf16 v[48:63], v[172:175], v[104:107], v[48:63]
	s_waitcnt lgkmcnt(0)
	v_mfma_f32_32x32x16_bf16 v[48:63], v[234:237], v[108:111], v[48:63]
	ds_read_b64_tr_b16 v[128:129], v209 offset:55296
	ds_read_b64_tr_b16 v[130:131], v209 offset:56832
	ds_read_b64_tr_b16 v[134:135], v209 offset:56896
	ds_read_b64_tr_b16 v[132:133], v209 offset:55360
	s_nop 11
	v_fma_f32 v48, v170, |v239|, v48
	v_fma_f32 v49, v170, |v240|, v49
	v_fma_f32 v50, v170, |v241|, v50
	v_fma_f32 v51, v170, |v242|, v51
	v_fma_f32 v52, v170, |v230|, v52
	v_fma_f32 v53, v170, |v231|, v53
	v_exp_f32_e32 v173, v49
	v_mov_b32_e32 v49, v53
	v_exp_f32_e32 v231, v49
	v_add_f32_e32 v49, 0xc1b00000, v171
	v_exp_f32_e32 v174, v50
	v_fma_f32 v49, v170, |v49|, v54
	v_exp_f32_e32 v172, v48
	v_exp_f32_e32 v232, v49
	v_add_f32_e32 v49, 0xc1a80000, v171
	v_fma_f32 v49, v170, |v49|, v55
	v_exp_f32_e32 v175, v51
	v_exp_f32_e32 v230, v52
	v_add_f32_e32 v48, 0, v172
	v_exp_f32_e32 v55, v49
	v_add_f32_e32 v49, 0xc1800000, v171
	v_add_f32_e32 v48, v173, v48
	v_add_f32_e32 v48, v174, v48
	v_fma_f32 v49, v170, |v49|, v56
	v_add_f32_e32 v48, v175, v48
	v_add_f32_e32 v48, v230, v48
	v_exp_f32_e32 v233, v49
	v_add_f32_e32 v48, v231, v48
	v_add_f32_e32 v48, v232, v48
	v_add_f32_e32 v48, v55, v48
	v_add_f32_e32 v234, v233, v48
	v_add_f32_e32 v48, 0xc1700000, v171
	v_fma_f32 v48, v170, |v48|, v57
	v_exp_f32_e32 v235, v48
	v_add_f32_e32 v48, 0xc1600000, v171
	v_fma_f32 v48, v170, |v48|, v58
	v_exp_f32_e32 v236, v48
	v_add_f32_e32 v48, 0xc1500000, v171
	v_fma_f32 v48, v170, |v48|, v59
	v_exp_f32_e32 v237, v48
	v_add_f32_e32 v48, 0xc1000000, v171
	v_fma_f32 v48, v170, |v48|, v60
	v_exp_f32_e32 v60, v48
	v_add_f32_e32 v48, 0xc0e00000, v171
	v_fma_f32 v48, v170, |v48|, v61
	v_exp_f32_e32 v61, v48
	v_add_f32_e32 v48, 0xc0c00000, v171
	v_fma_f32 v52, v170, |v48|, v62
	v_exp_f32_e32 v62, v52
	v_add_f32_e32 v239, 0xc0a00000, v171
	v_cvt_pk_bf16_f32 v52, v172, v173
	v_cvt_pk_bf16_f32 v53, v174, v175
	v_cvt_pk_bf16_f32 v54, v230, v231
	v_cvt_pk_bf16_f32 v55, v232, v55
	s_waitcnt lgkmcnt(2)
	s_nop 0
	v_mfma_f32_32x32x16_bf16 v[16:31], v[128:131], v[52:55], v[16:31]
	v_fma_f32 v63, v170, |v239|, v63
	ds_read_b64_tr_b16 v[48:49], v209 offset:58368
	ds_read_b64_tr_b16 v[50:51], v209 offset:59904
	v_exp_f32_e32 v63, v63
	s_waitcnt lgkmcnt(2)
	v_mfma_f32_32x32x16_bf16 v[0:15], v[132:135], v[52:55], v[0:15]
	ds_read_b64_tr_b16 v[58:59], v209 offset:59968
	ds_read_b64_tr_b16 v[56:57], v209 offset:58432
	v_cvt_pk_bf16_f32 v52, v233, v235
	v_cvt_pk_bf16_f32 v53, v236, v237
	v_cvt_pk_bf16_f32 v54, v60, v61
	v_cvt_pk_bf16_f32 v55, v62, v63
	s_waitcnt lgkmcnt(2)
	s_nop 0
	v_mfma_f32_32x32x16_bf16 v[16:31], v[48:51], v[52:55], v[16:31]
	v_add_f32_e32 v48, v235, v234
	v_add_f32_e32 v48, v236, v48
	v_add_f32_e32 v48, v237, v48
	v_add_f32_e32 v48, v60, v48
	v_add_f32_e32 v48, v61, v48
	v_add_f32_e32 v48, v62, v48
	v_add_f32_e32 v48, v63, v48
	s_waitcnt lgkmcnt(0)
	v_mfma_f32_32x32x16_bf16 v[0:15], v[56:59], v[52:55], v[0:15]
	v_add_f32_e32 v238, v238, v48
.Lattn2_skip1:
	ds_read_b128 v[172:175], v210
	ds_read_b128 v[230:233], v210 offset:32
	v_add_f32_e32 v239, 1.0, v171
	s_waitcnt lgkmcnt(1)
	v_mfma_f32_32x32x16_bf16 v[48:63], v[172:175], v[96:99], v[32:47]
	ds_read_b128 v[172:175], v210 offset:64
	ds_read_b128 v[234:237], v210 offset:96
	s_waitcnt lgkmcnt(2)
	v_mfma_f32_32x32x16_bf16 v[48:63], v[230:233], v[100:103], v[48:63]
	v_add_f32_e32 v230, 2.0, v171
	v_add_f32_e32 v231, 0x40400000, v171
	v_add_f32_e32 v232, 0x41000000, v171
	s_waitcnt lgkmcnt(1)
	v_mfma_f32_32x32x16_bf16 v[48:63], v[172:175], v[104:107], v[48:63]
	v_add_f32_e32 v233, 0x41100000, v171
	s_waitcnt lgkmcnt(0)
	v_mfma_f32_32x32x16_bf16 v[48:63], v[234:237], v[108:111], v[48:63]
	ds_read_b64_tr_b16 v[128:129], v211 offset:55296
	ds_read_b64_tr_b16 v[130:131], v211 offset:56832
	ds_read_b64_tr_b16 v[134:135], v211 offset:56896
	ds_read_b64_tr_b16 v[132:133], v211 offset:55360
	s_nop 11
	v_fma_f32 v48, v170, |v171|, v48
	v_fma_f32 v49, v170, |v239|, v49
	v_fma_f32 v50, v170, |v230|, v50
	v_fma_f32 v51, v170, |v231|, v51
	v_fma_f32 v52, v170, |v232|, v52
	v_fma_f32 v53, v170, |v233|, v53
	v_exp_f32_e32 v173, v49
	v_mov_b32_e32 v49, v53
	v_exp_f32_e32 v231, v49
	v_add_f32_e32 v49, 0x41200000, v171
	v_exp_f32_e32 v174, v50
	v_fma_f32 v49, v170, |v49|, v54
	v_exp_f32_e32 v172, v48
	v_exp_f32_e32 v232, v49
	v_add_f32_e32 v49, 0x41300000, v171
	v_fma_f32 v49, v170, |v49|, v55
	v_exp_f32_e32 v175, v51
	v_exp_f32_e32 v230, v52
	v_add_f32_e32 v48, 0, v172
	v_exp_f32_e32 v55, v49
	v_add_f32_e32 v49, 0x41800000, v171
	v_add_f32_e32 v48, v173, v48
	v_add_f32_e32 v48, v174, v48
	v_fma_f32 v49, v170, |v49|, v56
	v_add_f32_e32 v48, v175, v48
	v_add_f32_e32 v48, v230, v48
	v_exp_f32_e32 v233, v49
	v_add_f32_e32 v48, v231, v48
	v_add_f32_e32 v48, v232, v48
	v_add_f32_e32 v48, v55, v48
	v_add_f32_e32 v234, v233, v48
	v_add_f32_e32 v48, 0x41880000, v171
	v_fma_f32 v48, v170, |v48|, v57
	v_exp_f32_e32 v235, v48
	v_add_f32_e32 v48, 0x41900000, v171
	v_fma_f32 v48, v170, |v48|, v58
	v_exp_f32_e32 v236, v48
	v_add_f32_e32 v48, 0x41980000, v171
	v_fma_f32 v48, v170, |v48|, v59
	v_exp_f32_e32 v237, v48
	v_add_f32_e32 v48, 0x41c00000, v171
	v_fma_f32 v48, v170, |v48|, v60
	v_exp_f32_e32 v60, v48
	v_add_f32_e32 v48, 0x41c80000, v171
	v_fma_f32 v48, v170, |v48|, v61
	v_exp_f32_e32 v61, v48
	v_add_f32_e32 v48, 0x41d00000, v171
	v_fma_f32 v52, v170, |v48|, v62
	v_exp_f32_e32 v62, v52
	v_add_f32_e32 v239, 0x41d80000, v171
	v_cvt_pk_bf16_f32 v52, v172, v173
	v_cvt_pk_bf16_f32 v53, v174, v175
	v_cvt_pk_bf16_f32 v54, v230, v231
	v_cvt_pk_bf16_f32 v55, v232, v55
	s_waitcnt lgkmcnt(2)
; #define LAS __attribute__((address_space(3)))
; __device__ __forceinline__ unsigned pk2(float lo, float hi) { f32x2_t v = {lo, hi}; bf16x2_t b = __builtin_convertvector(v, bf16x2_t); return __builtin_bit_cast(unsigned, b); }
; __device__ __forceinline__ s16x4 trrd(LAS const unsigned char* p) { return __builtin_bit_cast(s16x4, __builtin_amdgcn_ds_read_tr16_b64_v4i16((LAS v4i16_t*)p)); }
; template <bool FUSED> __device__ __forceinline__ void attn_phase(const Args& a, LAS unsigned char* lds, int tid, int lane, int wave) {
;     ...
;         for (int j = 0; j < 5; ++j) {
;             f32x16 st;
; #pragma unroll
;             for (int i = 0; i < 16; ++i) st[i] = -mb;
;             LAS const unsigned char* kp = lds + (32 * wave + 32 * j + l31) * KP + 16 * h;
; #pragma unroll
;             for (int ks = 0; ks < 4; ++ks) { const bf16x8 kf = *(LAS const bf16x8*)(kp + 32 * ks); st = __builtin_amdgcn_mfma_f32_32x32x16_bf16(kf, qf[ks], st, 0, 0, 0); }
;             sum += attn_tile_exp(st, j, tlf, bsl, rlo, rhi);
; #pragma unroll
;             for (int s2 = 0; s2 < 2; ++s2) { u32x4 pw; pw.x = pk2(st[8 * s2 + 0], st[8 * s2 + 1]); pw.y = pk2(st[8 * s2 + 2], st[8 * s2 + 3]); pw.z = pk2(st[8 * s2 + 4], st[8 * s2 + 5]); pw.w = pk2(st[8 * s2 + 6], st[8 * s2 + 7]);
;                 const bf16x8 pf = __builtin_bit_cast(bf16x8, pw);
;                 LAS const unsigned char* vp = lds + LDS_VOFF + (32 * wave + 32 * j + 16 * s2 + 4 * h + q) * VP + 32 * blk + 8 * p;
; #pragma unroll
;                 for (int dt = 0; dt < 2; ++dt) { const s16x4 lo = trrd(vp + dt * 64), hi = trrd(vp + 8 * VP + dt * 64);
;                     const bf16x8 vf = __builtin_shufflevector(lo, hi, 0, 1, 2, 3, 4, 5, 6, 7);
;                     o[dt] = __builtin_amdgcn_mfma_f32_32x32x16_bf16(vf, pf, o[dt], 0, 0, 0); } }
;             __builtin_amdgcn_sched_barrier(0);
;         }
	s_nop 0
	v_mfma_f32_32x32x16_bf16 v[16:31], v[128:131], v[52:55], v[16:31]
	v_fma_f32 v63, v170, |v239|, v63
	ds_read_b64_tr_b16 v[48:49], v211 offset:58368
	ds_read_b64_tr_b16 v[50:51], v211 offset:59904
	v_exp_f32_e32 v63, v63
	s_waitcnt lgkmcnt(2)
	v_mfma_f32_32x32x16_bf16 v[0:15], v[132:135], v[52:55], v[0:15]
	ds_read_b64_tr_b16 v[58:59], v211 offset:59968
	ds_read_b64_tr_b16 v[56:57], v211 offset:58432
	v_cvt_pk_bf16_f32 v52, v233, v235
	v_cvt_pk_bf16_f32 v53, v236, v237
	v_cvt_pk_bf16_f32 v54, v60, v61
	v_cvt_pk_bf16_f32 v55, v62, v63
	s_waitcnt lgkmcnt(2)
	s_nop 0
	v_mfma_f32_32x32x16_bf16 v[16:31], v[48:51], v[52:55], v[16:31]
	v_add_f32_e32 v48, v235, v234
	v_add_f32_e32 v48, v236, v48
	v_add_f32_e32 v48, v237, v48
	v_add_f32_e32 v48, v60, v48
	v_add_f32_e32 v48, v61, v48
	v_add_f32_e32 v48, v62, v48
	v_add_f32_e32 v48, v63, v48
	s_waitcnt lgkmcnt(0)
	v_mfma_f32_32x32x16_bf16 v[0:15], v[56:59], v[52:55], v[0:15]
	v_add_f32_e32 v238, v238, v48
	s_cmp_gt_i32 s98, s99
	s_cbranch_scc1 .Lattn2_skip3
	ds_read_b128 v[172:175], v212
	ds_read_b128 v[230:233], v212 offset:32
	v_add_f32_e32 v239, 0x42000000, v171
	v_add_f32_e32 v240, 0x42040000, v171
	s_waitcnt lgkmcnt(1)
	v_mfma_f32_32x32x16_bf16 v[48:63], v[172:175], v[96:99], v[32:47]
	ds_read_b128 v[172:175], v212 offset:64
	ds_read_b128 v[234:237], v212 offset:96
	v_add_f32_e32 v241, 0x42080000, v171
	v_add_f32_e32 v242, 0x420c0000, v171
	s_waitcnt lgkmcnt(2)
	v_mfma_f32_32x32x16_bf16 v[48:63], v[230:233], v[100:103], v[48:63]
	v_add_f32_e32 v230, 0x42200000, v171
	v_add_f32_e32 v231, 0x42240000, v171
	s_waitcnt lgkmcnt(1)
	v_mfma_f32_32x32x16_bf16 v[48:63], v[172:175], v[104:107], v[48:63]
	s_waitcnt lgkmcnt(0)
	v_mfma_f32_32x32x16_bf16 v[48:63], v[234:237], v[108:111], v[48:63]
	ds_read_b64_tr_b16 v[128:129], v213 offset:55296
	ds_read_b64_tr_b16 v[130:131], v213 offset:56832
	ds_read_b64_tr_b16 v[134:135], v213 offset:56896
	ds_read_b64_tr_b16 v[132:133], v213 offset:55360
	s_nop 11
	v_fma_f32 v48, v170, |v239|, v48
	v_fma_f32 v49, v170, |v240|, v49
	v_fma_f32 v50, v170, |v241|, v50
	v_fma_f32 v51, v170, |v242|, v51
	v_fma_f32 v52, v170, |v230|, v52
	v_fma_f32 v53, v170, |v231|, v53
	v_exp_f32_e32 v173, v49
	v_mov_b32_e32 v49, v53
	v_exp_f32_e32 v231, v49
	v_add_f32_e32 v49, 0x42280000, v171
	v_exp_f32_e32 v174, v50
	v_fma_f32 v49, v170, |v49|, v54
	v_exp_f32_e32 v172, v48
	v_exp_f32_e32 v232, v49
	v_add_f32_e32 v49, 0x422c0000, v171
	v_fma_f32 v49, v170, |v49|, v55
	v_exp_f32_e32 v175, v51
	v_exp_f32_e32 v230, v52
	v_add_f32_e32 v48, 0, v172
	v_exp_f32_e32 v55, v49
	v_add_f32_e32 v49, 0x42400000, v171
	v_add_f32_e32 v48, v173, v48
	v_add_f32_e32 v48, v174, v48
	v_fma_f32 v49, v170, |v49|, v56
	v_add_f32_e32 v48, v175, v48
	v_add_f32_e32 v48, v230, v48
	v_exp_f32_e32 v233, v49
	v_add_f32_e32 v48, v231, v48
	v_add_f32_e32 v48, v232, v48
	v_add_f32_e32 v48, v55, v48
	v_add_f32_e32 v234, v233, v48
	v_add_f32_e32 v48, 0x42440000, v171
	v_fma_f32 v48, v170, |v48|, v57
	v_exp_f32_e32 v235, v48
	v_add_f32_e32 v48, 0x42480000, v171
	v_fma_f32 v48, v170, |v48|, v58
	v_exp_f32_e32 v236, v48
	v_add_f32_e32 v48, 0x424c0000, v171
	v_fma_f32 v48, v170, |v48|, v59
	v_exp_f32_e32 v237, v48
	v_add_f32_e32 v48, 0x42600000, v171
	v_fma_f32 v48, v170, |v48|, v60
	v_exp_f32_e32 v60, v48
	v_add_f32_e32 v48, 0x42640000, v171
	v_fma_f32 v48, v170, |v48|, v61
	v_exp_f32_e32 v61, v48
	v_add_f32_e32 v48, 0x42680000, v171
	v_fma_f32 v52, v170, |v48|, v62
	v_exp_f32_e32 v62, v52
	v_add_f32_e32 v239, 0x426c0000, v171
	v_cvt_pk_bf16_f32 v52, v172, v173
	v_cvt_pk_bf16_f32 v53, v174, v175
	v_cvt_pk_bf16_f32 v54, v230, v231
	v_cvt_pk_bf16_f32 v55, v232, v55
	s_waitcnt lgkmcnt(2)
	s_nop 0
	v_mfma_f32_32x32x16_bf16 v[16:31], v[128:131], v[52:55], v[16:31]
	v_fma_f32 v63, v170, |v239|, v63
	ds_read_b64_tr_b16 v[48:49], v213 offset:58368
	ds_read_b64_tr_b16 v[50:51], v213 offset:59904
	v_exp_f32_e32 v63, v63
	s_waitcnt lgkmcnt(2)
	v_mfma_f32_32x32x16_bf16 v[0:15], v[132:135], v[52:55], v[0:15]
	ds_read_b64_tr_b16 v[58:59], v213 offset:59968
	ds_read_b64_tr_b16 v[56:57], v213 offset:58432
	v_cvt_pk_bf16_f32 v52, v233, v235
	v_cvt_pk_bf16_f32 v53, v236, v237
	v_cvt_pk_bf16_f32 v54, v60, v61
	v_cvt_pk_bf16_f32 v55, v62, v63
	s_waitcnt lgkmcnt(2)
	s_nop 0
	v_mfma_f32_32x32x16_bf16 v[16:31], v[48:51], v[52:55], v[16:31]
	v_add_f32_e32 v48, v235, v234
	v_add_f32_e32 v48, v236, v48
	v_add_f32_e32 v48, v237, v48
	v_add_f32_e32 v48, v60, v48
	v_add_f32_e32 v48, v61, v48
	v_add_f32_e32 v48, v62, v48
	v_add_f32_e32 v48, v63, v48
	s_waitcnt lgkmcnt(0)
	v_mfma_f32_32x32x16_bf16 v[0:15], v[56:59], v[52:55], v[0:15]
	v_add_f32_e32 v60, v238, v48
	s_branch .Lattn2_t4f

; #define LAS __attribute__((address_space(3)))
; __device__ __forceinline__ unsigned pk2(float lo, float hi) { f32x2_t v = {lo, hi}; bf16x2_t b = __builtin_convertvector(v, bf16x2_t); return __builtin_bit_cast(unsigned, b); }
; __device__ __forceinline__ s16x4 trrd(LAS const unsigned char* p) { return __builtin_bit_cast(s16x4, __builtin_amdgcn_ds_read_tr16_b64_v4i16((LAS v4i16_t*)p)); }
; template <bool FUSED> __device__ __forceinline__ void attn_phase(const Args& a, LAS unsigned char* lds, int tid, int lane, int wave) {
;     ...
;         for (int j = 0; j < 5; ++j) {
;             f32x16 st;
; #pragma unroll
;             for (int i = 0; i < 16; ++i) st[i] = -mb;
;             LAS const unsigned char* kp = lds + (32 * wave + 32 * j + l31) * KP + 16 * h;
; #pragma unroll
;             for (int ks = 0; ks < 4; ++ks) { const bf16x8 kf = *(LAS const bf16x8*)(kp + 32 * ks); st = __builtin_amdgcn_mfma_f32_32x32x16_bf16(kf, qf[ks], st, 0, 0, 0); }
;             sum += attn_tile_exp(st, j, tlf, bsl, rlo, rhi);
; #pragma unroll
;             for (int s2 = 0; s2 < 2; ++s2) { u32x4 pw; pw.x = pk2(st[8 * s2 + 0], st[8 * s2 + 1]); pw.y = pk2(st[8 * s2 + 2], st[8 * s2 + 3]); pw.z = pk2(st[8 * s2 + 4], st[8 * s2 + 5]); pw.w = pk2(st[8 * s2 + 6], st[8 * s2 + 7]);
;                 const bf16x8 pf = __builtin_bit_cast(bf16x8, pw);
;                 LAS const unsigned char* vp = lds + LDS_VOFF + (32 * wave + 32 * j + 16 * s2 + 4 * h + q) * VP + 32 * blk + 8 * p;
; #pragma unroll
;                 for (int dt = 0; dt < 2; ++dt) { const s16x4 lo = trrd(vp + dt * 64), hi = trrd(vp + 8 * VP + dt * 64);
;                     const bf16x8 vf = __builtin_shufflevector(lo, hi, 0, 1, 2, 3, 4, 5, 6, 7);
;                     o[dt] = __builtin_amdgcn_mfma_f32_32x32x16_bf16(vf, pf, o[dt], 0, 0, 0); } }
;             __builtin_amdgcn_sched_barrier(0);
;         }
.Lattn2_t4f:
	s_sub_i32 s99, s99, 32
	s_cmp_gt_i32 s98, s99
	s_cbranch_scc1 .Lattn2_skip4
	ds_read_b128 v[48:51], v214
	ds_read_b128 v[52:55], v214 offset:32
	s_waitcnt lgkmcnt(1)
	v_mfma_f32_32x32x16_bf16 v[32:47], v[48:51], v[96:99], v[32:47]
	ds_read_b128 v[48:51], v214 offset:64
	ds_read_b128 v[56:59], v214 offset:96
	s_waitcnt lgkmcnt(2)
	v_mfma_f32_32x32x16_bf16 v[32:47], v[52:55], v[100:103], v[32:47]
	s_waitcnt lgkmcnt(1)
	v_mfma_f32_32x32x16_bf16 v[32:47], v[48:51], v[104:107], v[32:47]
	s_waitcnt lgkmcnt(0)
	v_mfma_f32_32x32x16_bf16 v[32:47], v[56:59], v[108:111], v[32:47]
	ds_read_b64_tr_b16 v[128:129], v215 offset:55296
	ds_read_b64_tr_b16 v[130:131], v215 offset:56832
	ds_read_b64_tr_b16 v[134:135], v215 offset:56896
	ds_read_b64_tr_b16 v[132:133], v215 offset:55360
	s_nop 11
	v_fma_f32 v32, v170, |v244|, v32
	v_fma_f32 v33, v170, |v245|, v33
	v_fma_f32 v34, v170, |v246|, v34
	v_fma_f32 v35, v170, |v247|, v35
	v_fma_f32 v36, v170, |v248|, v36
	v_fma_f32 v37, v170, |v249|, v37
	v_exp_f32_e32 v49, v33
	v_mov_b32_e32 v33, v37
	v_exp_f32_e32 v53, v33
	v_exp_f32_e32 v50, v34
	v_fma_f32 v33, v170, |v250|, v38
	v_exp_f32_e32 v48, v32
	v_exp_f32_e32 v54, v33
	v_fma_f32 v33, v170, |v251|, v39
	v_exp_f32_e32 v51, v35
	v_exp_f32_e32 v52, v36
	v_add_f32_e32 v32, 0, v48
	v_exp_f32_e32 v39, v33
	v_add_f32_e32 v32, v49, v32
	v_add_f32_e32 v32, v50, v32
	v_fma_f32 v33, v170, |v252|, v40
	v_add_f32_e32 v32, v51, v32
	v_add_f32_e32 v32, v52, v32
	v_exp_f32_e32 v55, v33
	v_add_f32_e32 v32, v53, v32
	v_add_f32_e32 v32, v54, v32
	v_add_f32_e32 v32, v39, v32
	v_add_f32_e32 v56, v55, v32
	v_fma_f32 v32, v170, |v253|, v41
	v_exp_f32_e32 v57, v32
	v_fma_f32 v32, v170, |v254|, v42
	v_exp_f32_e32 v58, v32
	v_fma_f32 v32, v170, |v255|, v43
	v_exp_f32_e32 v59, v32
	v_fma_f32 v32, v170, |v164|, v44
	v_exp_f32_e32 v44, v32
	v_fma_f32 v32, v170, |v165|, v45
	v_exp_f32_e32 v45, v32
	v_fma_f32 v36, v170, |v166|, v46
	v_exp_f32_e32 v46, v36
	v_cvt_pk_bf16_f32 v36, v48, v49
	v_cvt_pk_bf16_f32 v37, v50, v51
	v_cvt_pk_bf16_f32 v38, v52, v53
	v_cvt_pk_bf16_f32 v39, v54, v39
	s_waitcnt lgkmcnt(2)
	s_nop 0
	v_mfma_f32_32x32x16_bf16 v[16:31], v[128:131], v[36:39], v[16:31]
	v_fma_f32 v47, v170, |v167|, v47
	ds_read_b64_tr_b16 v[32:33], v215 offset:58368
	ds_read_b64_tr_b16 v[34:35], v215 offset:59904
	v_exp_f32_e32 v47, v47
	s_waitcnt lgkmcnt(2)
	v_mfma_f32_32x32x16_bf16 v[0:15], v[132:135], v[36:39], v[0:15]
	ds_read_b64_tr_b16 v[42:43], v215 offset:59968
	ds_read_b64_tr_b16 v[40:41], v215 offset:58432
	v_cvt_pk_bf16_f32 v36, v55, v57
	v_cvt_pk_bf16_f32 v37, v58, v59
	v_cvt_pk_bf16_f32 v38, v44, v45
	v_cvt_pk_bf16_f32 v39, v46, v47
	s_waitcnt lgkmcnt(2)
	s_nop 0
	v_mfma_f32_32x32x16_bf16 v[16:31], v[32:35], v[36:39], v[16:31]
	v_add_f32_e32 v32, v57, v56
	v_add_f32_e32 v32, v58, v32
	v_add_f32_e32 v32, v59, v32
	v_add_f32_e32 v32, v44, v32
	v_add_f32_e32 v32, v45, v32
	v_add_f32_e32 v32, v46, v32
	v_add_f32_e32 v32, v47, v32
	s_waitcnt lgkmcnt(0)
	v_mfma_f32_32x32x16_bf16 v[0:15], v[40:43], v[36:39], v[0:15]
	v_add_f32_e32 v236, v60, v32
	s_branch .Lattn2_end
